# hyena filter LDS-fill loop: 3 iterations of loads in flight with counted waits
# baseline (speedup 1.0000x reference)
; #define LAS __attribute__((address_space(3)))
; __device__ __forceinline__ float block_sum(float v, LAS float* RED, int tid) {
;     v = wave_sum(v); __syncthreads(); if ((tid & 63) == 0) RED[tid >> 6] = v; __syncthreads();
;     float s = 0.f;
; #pragma unroll
;     for (int w = 0; w < 8; ++w) s += RED[w];
;     return s;
; __global__ void __launch_bounds__(NTHR, 2) fwd_mega(Args a) {
;     ...
;                     s = block_sum(s, RED, tid); const float inv = 1.0f / (s + EPSF);
;                     for (int i = tid; i < 8192; i += NTHR) { X[PX(i)] = mk2(hf[i] * inv, 0.f); X[PX(8192 + i)] = (i == 0) ? mk2(0.f, 0.f) : mk2(hb[8192 - i] * inv, 0.f); }
.LBB0_513:
	s_or_b64 exec, exec, s[6:7]
	v_add_f32_dpp v1, v1, v1 quad_perm:[1,0,3,2] row_mask:0xf bank_mask:0xf bound_ctrl:1
	s_xor_b64 s[36:37], s[46:47], -1
	s_nop 0
	v_add_f32_dpp v1, v1, v1 quad_perm:[2,3,0,1] row_mask:0xf bank_mask:0xf bound_ctrl:1
	s_barrier
	s_nop 0
	v_add_f32_dpp v1, v1, v1 row_half_mirror row_mask:0xf bank_mask:0xf bound_ctrl:1
	s_nop 1
	v_add_f32_dpp v1, v1, v1 row_mirror row_mask:0xf bank_mask:0xf bound_ctrl:1
	v_mov_b32_e32 v4, v1
	s_nop 1
	v_permlane16_swap_b32_e32 v1, v4
	v_add_f32_e32 v1, v1, v4
	v_mov_b32_e32 v4, v1
	s_nop 1
	v_permlane32_swap_b32_e32 v1, v4
	s_and_saveexec_b64 s[6:7], s[40:41]
	v_add_f32_e32 v1, v1, v4
	v_add_u32_e32 v4, 0, v154
	v_add_u32_e32 v4, 0x21000, v4
	ds_write_b32 v4, v1
	s_or_b64 exec, exec, s[6:7]
	s_waitcnt lgkmcnt(0)
	s_barrier
	s_and_saveexec_b64 s[6:7], s[38:39]
	s_cbranch_execz .LBB0_520
	s_add_i32 s10, 0, 0x21000
	v_mov_b32_e32 v1, s10
	ds_read_b128 v[4:7], v1
	s_mov_b32 s49, s64
	s_waitcnt lgkmcnt(0)
	v_add_f32_e32 v1, 0, v4
	v_add_f32_e32 v1, v1, v5
	v_add_f32_e32 v1, v1, v6
	v_mov_b32_e32 v4, s56
	v_add_f32_e32 v1, v1, v7
	ds_read_b128 v[4:7], v4
	s_waitcnt lgkmcnt(0)
	v_add_f32_e32 v1, v1, v4
	v_add_f32_e32 v1, v1, v5
	v_add_f32_e32 v1, v1, v6
	v_add_f32_e32 v1, v1, v7
	v_add_f32_e32 v1, 0x358637bd, v1
	v_div_scale_f32 v4, s[10:11], v1, v1, 1.0
	v_rcp_f32_e32 v5, v4
	s_lshl_b32 s10, s48, 8
	s_bitset1_b32 s10, 9
	s_add_u32 s10, s10, s14
	v_fma_f32 v6, -v4, v5, 1.0
	v_fmac_f32_e32 v5, v6, v5
	v_div_scale_f32 v6, vcc, 1.0, v1, 1.0
	s_addc_u32 s11, 0, s15
	v_mul_f32_e32 v7, v6, v5
	s_lshl_b64 s[10:11], s[10:11], 15
	v_fma_f32 v8, -v4, v7, v6
	s_add_u32 s4, s4, s10
	v_fmac_f32_e32 v7, v8, v5
	s_addc_u32 s5, s5, s11
	v_fma_f32 v4, -v4, v7, v6
	s_add_u32 s4, s4, 0x1e00000
	v_div_fmas_f32 v4, v4, v5, v7
	s_addc_u32 s5, s5, 0
	s_lshl_b64 s[10:11], s[48:49], 23
	v_div_fixup_f32 v1, v4, v1, 1.0
	v_lshl_add_u64 v[2:3], v[2:3], 0, s[10:11]
	s_mov_b64 s[10:11], 0
	v_mov_b32_e32 v6, v163
	v_mov_b32_e32 v4, v162
	v_mov_b32_e32 v7, v16
	s_mov_b32 s23, 0x10000
	v_mov_b32_e32 v5, v209
	v_lshl_add_u64 v[8:9], v[4:5], 2, s[4:5]
	global_load_dword v10, v[2:3], off
	global_load_dword v13, v[8:9], off
	v_lshl_add_u64 v[2:3], v[2:3], 0, s[16:17]
	global_load_dword v11, v[2:3], off
	global_load_dword v14, v[8:9], off offset:-2048
	v_lshl_add_u64 v[2:3], v[2:3], 0, s[16:17]
	global_load_dword v12, v[2:3], off
	global_load_dword v15, v[8:9], off offset:-4096
	v_lshl_add_u64 v[2:3], v[2:3], 0, s[16:17]
	v_add_u32_e32 v4, -1536, v4
	v_cmp_ne_u32_e32 vcc, 0, v7
	v_ashrrev_i32_e32 v8, 6, v7
	v_lshl_add_u32 v8, v8, 3, v6
	s_waitcnt vmcnt(5) lgkmcnt(0)
	v_mul_f32_e32 v208, v1, v10
	ds_write_b64 v8, v[208:209]
	v_add_u32_e32 v5, 0x2000, v7
	v_ashrrev_i32_e32 v5, 6, v5
	v_lshlrev_b32_e32 v5, 3, v5
	v_add3_u32 v5, v6, v5, s23
	s_waitcnt vmcnt(4)
	v_mul_f32_e32 v208, v1, v13
	v_cndmask_b32_e32 v208, 0, v208, vcc
	ds_write_b64 v5, v[208:209]
	v_add_u32_e32 v6, 0x1000, v6
	v_add_u32_e32 v7, 0x200, v7
	v_cmp_ne_u32_e32 vcc, 0, v7
	v_ashrrev_i32_e32 v8, 6, v7
	v_lshl_add_u32 v8, v8, 3, v6
	s_waitcnt vmcnt(3) lgkmcnt(0)
	v_mul_f32_e32 v208, v1, v11
	ds_write_b64 v8, v[208:209]
	v_add_u32_e32 v5, 0x2000, v7
	v_ashrrev_i32_e32 v5, 6, v5
	v_lshlrev_b32_e32 v5, 3, v5
	v_add3_u32 v5, v6, v5, s23
	s_waitcnt vmcnt(2)
	v_mul_f32_e32 v208, v1, v14
	v_cndmask_b32_e32 v208, 0, v208, vcc
	ds_write_b64 v5, v[208:209]
	v_add_u32_e32 v6, 0x1000, v6
	v_add_u32_e32 v7, 0x200, v7
	v_cmp_ne_u32_e32 vcc, 0, v7
	v_ashrrev_i32_e32 v8, 6, v7
	v_lshl_add_u32 v8, v8, 3, v6
	s_waitcnt vmcnt(1) lgkmcnt(0)
	v_mul_f32_e32 v208, v1, v12
	ds_write_b64 v8, v[208:209]
	v_add_u32_e32 v5, 0x2000, v7
	v_ashrrev_i32_e32 v5, 6, v5
	v_lshlrev_b32_e32 v5, 3, v5
	v_add3_u32 v5, v6, v5, s23
	s_waitcnt vmcnt(0)
	v_mul_f32_e32 v208, v1, v15
	v_cndmask_b32_e32 v208, 0, v208, vcc
	ds_write_b64 v5, v[208:209]
	v_add_u32_e32 v6, 0x1000, v6
	v_add_u32_e32 v7, 0x200, v7
	v_mov_b32_e32 v5, v209
	v_lshl_add_u64 v[8:9], v[4:5], 2, s[4:5]
	global_load_dword v10, v[2:3], off
	global_load_dword v13, v[8:9], off
	v_lshl_add_u64 v[2:3], v[2:3], 0, s[16:17]
	global_load_dword v11, v[2:3], off
	global_load_dword v14, v[8:9], off offset:-2048
	v_lshl_add_u64 v[2:3], v[2:3], 0, s[16:17]
	global_load_dword v12, v[2:3], off
	global_load_dword v15, v[8:9], off offset:-4096
	v_lshl_add_u64 v[2:3], v[2:3], 0, s[16:17]
	v_add_u32_e32 v4, -1536, v4
	v_cmp_ne_u32_e32 vcc, 0, v7
	v_ashrrev_i32_e32 v8, 6, v7
	v_lshl_add_u32 v8, v8, 3, v6
	s_waitcnt vmcnt(5) lgkmcnt(0)
	v_mul_f32_e32 v208, v1, v10
	ds_write_b64 v8, v[208:209]
	v_add_u32_e32 v5, 0x2000, v7
	v_ashrrev_i32_e32 v5, 6, v5
	v_lshlrev_b32_e32 v5, 3, v5
	v_add3_u32 v5, v6, v5, s23
	s_waitcnt vmcnt(4)
	v_mul_f32_e32 v208, v1, v13
	v_cndmask_b32_e32 v208, 0, v208, vcc
	ds_write_b64 v5, v[208:209]
	v_add_u32_e32 v6, 0x1000, v6
	v_add_u32_e32 v7, 0x200, v7
	v_cmp_ne_u32_e32 vcc, 0, v7
	v_ashrrev_i32_e32 v8, 6, v7
	v_lshl_add_u32 v8, v8, 3, v6
	s_waitcnt vmcnt(3) lgkmcnt(0)
	v_mul_f32_e32 v208, v1, v11
	ds_write_b64 v8, v[208:209]
	v_add_u32_e32 v5, 0x2000, v7
	v_ashrrev_i32_e32 v5, 6, v5
	v_lshlrev_b32_e32 v5, 3, v5
	v_add3_u32 v5, v6, v5, s23
	s_waitcnt vmcnt(2)
	v_mul_f32_e32 v208, v1, v14
	v_cndmask_b32_e32 v208, 0, v208, vcc
	ds_write_b64 v5, v[208:209]
	v_add_u32_e32 v6, 0x1000, v6
	v_add_u32_e32 v7, 0x200, v7
	v_cmp_ne_u32_e32 vcc, 0, v7
	v_ashrrev_i32_e32 v8, 6, v7
	v_lshl_add_u32 v8, v8, 3, v6
	s_waitcnt vmcnt(1) lgkmcnt(0)
	v_mul_f32_e32 v208, v1, v12
	ds_write_b64 v8, v[208:209]
	v_add_u32_e32 v5, 0x2000, v7
	v_ashrrev_i32_e32 v5, 6, v5
	v_lshlrev_b32_e32 v5, 3, v5
	v_add3_u32 v5, v6, v5, s23
	s_waitcnt vmcnt(0)
; __global__ void __launch_bounds__(NTHR, 2) fwd_mega(Args a) {
;     ...
;                     for (int i = tid; i < 8192; i += NTHR) { X[PX(i)] = mk2(hf[i] * inv, 0.f); X[PX(8192 + i)] = (i == 0) ? mk2(0.f, 0.f) : mk2(hb[8192 - i] * inv, 0.f); }
	v_mul_f32_e32 v208, v1, v15
	v_cndmask_b32_e32 v208, 0, v208, vcc
	ds_write_b64 v5, v[208:209]
	v_add_u32_e32 v6, 0x1000, v6
	v_add_u32_e32 v7, 0x200, v7
	v_mov_b32_e32 v5, v209
	v_lshl_add_u64 v[8:9], v[4:5], 2, s[4:5]
	global_load_dword v10, v[2:3], off
	global_load_dword v13, v[8:9], off
	v_lshl_add_u64 v[2:3], v[2:3], 0, s[16:17]
	global_load_dword v11, v[2:3], off
	global_load_dword v14, v[8:9], off offset:-2048
	v_lshl_add_u64 v[2:3], v[2:3], 0, s[16:17]
	global_load_dword v12, v[2:3], off
	global_load_dword v15, v[8:9], off offset:-4096
	v_lshl_add_u64 v[2:3], v[2:3], 0, s[16:17]
	v_add_u32_e32 v4, -1536, v4
	v_cmp_ne_u32_e32 vcc, 0, v7
	v_ashrrev_i32_e32 v8, 6, v7
	v_lshl_add_u32 v8, v8, 3, v6
	s_waitcnt vmcnt(5) lgkmcnt(0)
	v_mul_f32_e32 v208, v1, v10
	ds_write_b64 v8, v[208:209]
	v_add_u32_e32 v5, 0x2000, v7
	v_ashrrev_i32_e32 v5, 6, v5
	v_lshlrev_b32_e32 v5, 3, v5
	v_add3_u32 v5, v6, v5, s23
	s_waitcnt vmcnt(4)
	v_mul_f32_e32 v208, v1, v13
	v_cndmask_b32_e32 v208, 0, v208, vcc
	ds_write_b64 v5, v[208:209]
	v_add_u32_e32 v6, 0x1000, v6
	v_add_u32_e32 v7, 0x200, v7
	v_cmp_ne_u32_e32 vcc, 0, v7
	v_ashrrev_i32_e32 v8, 6, v7
	v_lshl_add_u32 v8, v8, 3, v6
	s_waitcnt vmcnt(3) lgkmcnt(0)
	v_mul_f32_e32 v208, v1, v11
	ds_write_b64 v8, v[208:209]
	v_add_u32_e32 v5, 0x2000, v7
	v_ashrrev_i32_e32 v5, 6, v5
	v_lshlrev_b32_e32 v5, 3, v5
	v_add3_u32 v5, v6, v5, s23
	s_waitcnt vmcnt(2)
	v_mul_f32_e32 v208, v1, v14
	v_cndmask_b32_e32 v208, 0, v208, vcc
	ds_write_b64 v5, v[208:209]
	v_add_u32_e32 v6, 0x1000, v6
	v_add_u32_e32 v7, 0x200, v7
	v_cmp_ne_u32_e32 vcc, 0, v7
	v_ashrrev_i32_e32 v8, 6, v7
	v_lshl_add_u32 v8, v8, 3, v6
	s_waitcnt vmcnt(1) lgkmcnt(0)
	v_mul_f32_e32 v208, v1, v12
	ds_write_b64 v8, v[208:209]
	v_add_u32_e32 v5, 0x2000, v7
	v_ashrrev_i32_e32 v5, 6, v5
	v_lshlrev_b32_e32 v5, 3, v5
	v_add3_u32 v5, v6, v5, s23
	s_waitcnt vmcnt(0)
	v_mul_f32_e32 v208, v1, v15
	v_cndmask_b32_e32 v208, 0, v208, vcc
	ds_write_b64 v5, v[208:209]
	v_add_u32_e32 v6, 0x1000, v6
	v_add_u32_e32 v7, 0x200, v7
	v_mov_b32_e32 v5, v209
	v_lshl_add_u64 v[8:9], v[4:5], 2, s[4:5]
	global_load_dword v10, v[2:3], off
	global_load_dword v13, v[8:9], off
	v_lshl_add_u64 v[2:3], v[2:3], 0, s[16:17]
	global_load_dword v11, v[2:3], off
	global_load_dword v14, v[8:9], off offset:-2048
	v_lshl_add_u64 v[2:3], v[2:3], 0, s[16:17]
	global_load_dword v12, v[2:3], off
	global_load_dword v15, v[8:9], off offset:-4096
	v_lshl_add_u64 v[2:3], v[2:3], 0, s[16:17]
	v_add_u32_e32 v4, -1536, v4
	v_cmp_ne_u32_e32 vcc, 0, v7
	v_ashrrev_i32_e32 v8, 6, v7
	v_lshl_add_u32 v8, v8, 3, v6
	s_waitcnt vmcnt(5) lgkmcnt(0)
	v_mul_f32_e32 v208, v1, v10
	ds_write_b64 v8, v[208:209]
	v_add_u32_e32 v5, 0x2000, v7
	v_ashrrev_i32_e32 v5, 6, v5
	v_lshlrev_b32_e32 v5, 3, v5
	v_add3_u32 v5, v6, v5, s23
	s_waitcnt vmcnt(4)
	v_mul_f32_e32 v208, v1, v13
	v_cndmask_b32_e32 v208, 0, v208, vcc
	ds_write_b64 v5, v[208:209]
	v_add_u32_e32 v6, 0x1000, v6
	v_add_u32_e32 v7, 0x200, v7
	v_cmp_ne_u32_e32 vcc, 0, v7
	v_ashrrev_i32_e32 v8, 6, v7
	v_lshl_add_u32 v8, v8, 3, v6
	s_waitcnt vmcnt(3) lgkmcnt(0)
	v_mul_f32_e32 v208, v1, v11
	ds_write_b64 v8, v[208:209]
	v_add_u32_e32 v5, 0x2000, v7
	v_ashrrev_i32_e32 v5, 6, v5
	v_lshlrev_b32_e32 v5, 3, v5
	v_add3_u32 v5, v6, v5, s23
	s_waitcnt vmcnt(2)
	v_mul_f32_e32 v208, v1, v14
	v_cndmask_b32_e32 v208, 0, v208, vcc
	ds_write_b64 v5, v[208:209]
	v_add_u32_e32 v6, 0x1000, v6
	v_add_u32_e32 v7, 0x200, v7
	v_cmp_ne_u32_e32 vcc, 0, v7
	v_ashrrev_i32_e32 v8, 6, v7
	v_lshl_add_u32 v8, v8, 3, v6
	s_waitcnt vmcnt(1) lgkmcnt(0)
	v_mul_f32_e32 v208, v1, v12
	ds_write_b64 v8, v[208:209]
	v_add_u32_e32 v5, 0x2000, v7
	v_ashrrev_i32_e32 v5, 6, v5
	v_lshlrev_b32_e32 v5, 3, v5
	v_add3_u32 v5, v6, v5, s23
	s_waitcnt vmcnt(0)
	v_mul_f32_e32 v208, v1, v15
	v_cndmask_b32_e32 v208, 0, v208, vcc
	ds_write_b64 v5, v[208:209]
	v_add_u32_e32 v6, 0x1000, v6
	v_add_u32_e32 v7, 0x200, v7
	v_mov_b32_e32 v5, v209
	v_lshl_add_u64 v[8:9], v[4:5], 2, s[4:5]
	global_load_dword v10, v[2:3], off
	global_load_dword v13, v[8:9], off
	v_lshl_add_u64 v[2:3], v[2:3], 0, s[16:17]
	global_load_dword v11, v[2:3], off
	global_load_dword v14, v[8:9], off offset:-2048
	v_lshl_add_u64 v[2:3], v[2:3], 0, s[16:17]
	global_load_dword v12, v[2:3], off
	global_load_dword v15, v[8:9], off offset:-4096
	v_lshl_add_u64 v[2:3], v[2:3], 0, s[16:17]
	v_add_u32_e32 v4, -1536, v4
	v_cmp_ne_u32_e32 vcc, 0, v7
	v_ashrrev_i32_e32 v8, 6, v7
	v_lshl_add_u32 v8, v8, 3, v6
	s_waitcnt vmcnt(5) lgkmcnt(0)
	v_mul_f32_e32 v208, v1, v10
	ds_write_b64 v8, v[208:209]
	v_add_u32_e32 v5, 0x2000, v7
	v_ashrrev_i32_e32 v5, 6, v5
	v_lshlrev_b32_e32 v5, 3, v5
	v_add3_u32 v5, v6, v5, s23
	s_waitcnt vmcnt(4)
	v_mul_f32_e32 v208, v1, v13
	v_cndmask_b32_e32 v208, 0, v208, vcc
	ds_write_b64 v5, v[208:209]
	v_add_u32_e32 v6, 0x1000, v6
	v_add_u32_e32 v7, 0x200, v7
	v_cmp_ne_u32_e32 vcc, 0, v7
	v_ashrrev_i32_e32 v8, 6, v7
	v_lshl_add_u32 v8, v8, 3, v6
	s_waitcnt vmcnt(3) lgkmcnt(0)
	v_mul_f32_e32 v208, v1, v11
	ds_write_b64 v8, v[208:209]
	v_add_u32_e32 v5, 0x2000, v7
	v_ashrrev_i32_e32 v5, 6, v5
	v_lshlrev_b32_e32 v5, 3, v5
	v_add3_u32 v5, v6, v5, s23
	s_waitcnt vmcnt(2)
	v_mul_f32_e32 v208, v1, v14
	v_cndmask_b32_e32 v208, 0, v208, vcc
	ds_write_b64 v5, v[208:209]
	v_add_u32_e32 v6, 0x1000, v6
	v_add_u32_e32 v7, 0x200, v7
	v_cmp_ne_u32_e32 vcc, 0, v7
	v_ashrrev_i32_e32 v8, 6, v7
	v_lshl_add_u32 v8, v8, 3, v6
	s_waitcnt vmcnt(1) lgkmcnt(0)
	v_mul_f32_e32 v208, v1, v12
	ds_write_b64 v8, v[208:209]
	v_add_u32_e32 v5, 0x2000, v7
	v_ashrrev_i32_e32 v5, 6, v5
	v_lshlrev_b32_e32 v5, 3, v5
	v_add3_u32 v5, v6, v5, s23
	s_waitcnt vmcnt(0)
	v_mul_f32_e32 v208, v1, v15
	v_cndmask_b32_e32 v208, 0, v208, vcc
	ds_write_b64 v5, v[208:209]
	v_add_u32_e32 v6, 0x1000, v6
	v_add_u32_e32 v7, 0x200, v7
	v_mov_b32_e32 v5, v209
	v_lshl_add_u64 v[8:9], v[4:5], 2, s[4:5]
	global_load_dword v10, v[2:3], off
	global_load_dword v13, v[8:9], off
	v_lshl_add_u64 v[2:3], v[2:3], 0, s[16:17]
	v_add_u32_e32 v4, -512, v4
	v_cmp_ne_u32_e32 vcc, 0, v7
	v_ashrrev_i32_e32 v8, 6, v7
	v_lshl_add_u32 v8, v8, 3, v6
	s_waitcnt vmcnt(1) lgkmcnt(0)
	v_mul_f32_e32 v208, v1, v10
	ds_write_b64 v8, v[208:209]
	v_add_u32_e32 v5, 0x2000, v7
	v_ashrrev_i32_e32 v5, 6, v5
	v_lshlrev_b32_e32 v5, 3, v5
	v_add3_u32 v5, v6, v5, s23
	s_waitcnt vmcnt(0)
	v_mul_f32_e32 v208, v1, v13
	v_cndmask_b32_e32 v208, 0, v208, vcc
	ds_write_b64 v5, v[208:209]
	v_add_u32_e32 v6, 0x1000, v6
	v_add_u32_e32 v7, 0x200, v7
